# first seam uses a non-returning counter barrier instead of cg grid.sync; SB unit head waits only for pending loads (vmcnt(32))
# speedup vs baseline: 1.0319x; 1.0005x over previous
; __global__ void __launch_bounds__(NTHR, 2) fwd_kernel(Params p) {
;     ...
;     cg::grid_group grid = cg::this_grid();
.LBB0_156:
	v_lshrrev_b32_e32 v2, 20, v0
	v_lshrrev_b32_e32 v0, 10, v0
	s_waitcnt lgkmcnt(0)
	s_barrier
	s_waitcnt vmcnt(0) lgkmcnt(0)
	v_or_b32_e32 v0, v0, v2
	s_movk_i32 s0, 0x3ff
	v_and_or_b32 v0, v0, s0, v1
	v_cmp_eq_u32_e32 vcc, 0, v0
	s_barrier
	s_and_saveexec_b64 s[0:1], vcc
	s_cbranch_execz .LBB0_166
	buffer_wbl2 sc1
	s_waitcnt vmcnt(0)
	v_readlane_b32 s2, v254, 18
	v_readlane_b32 s3, v254, 19
	v_mov_b32_e32 v2, 0
	v_mov_b32_e32 v3, 1
	s_add_u32 s2, s2, 0x3d100040
	s_addc_u32 s3, s3, 0
	s_nop 4
	global_atomic_add v2, v3, s[2:3]
.Lfirstbar_poll:
	global_load_dword v3, v2, s[2:3] sc1
	s_waitcnt vmcnt(0)
	v_cmp_le_u32_e32 vcc, s33, v3
	s_cbranch_vccnz .Lfirstbar_done
	s_sleep 1
	s_branch .Lfirstbar_poll
.Lfirstbar_done:
	buffer_inv sc1
	s_waitcnt vmcnt(0)
	v_mov_b32_e32 v0, 0

; #define LAS __attribute__((address_space(3)))
; __device__ __forceinline__ int otid(int wv) { int t = (wv << 6) | (int)__builtin_amdgcn_mbcnt_hi(~0u, __builtin_amdgcn_mbcnt_lo(~0u, 0u)); asm volatile("" : "+v"(t)); return t; }
; template <class T> __device__ __forceinline__ T* uni(T* p) { unsigned long long v = (unsigned long long)p; asm volatile("" : "+s"(v)); return (T*)v; }
; __device__ NOINL void sb_unit(unsigned char* ws, LAS unsigned char* lds, int unit, int wv) {
;     ws = uni(ws); unit = __builtin_amdgcn_readfirstlane(unit);
;     const int tid = otid(wv), lane = tid & 63, wave = __builtin_amdgcn_readfirstlane(tid >> 6), fr = lane & 15, fq = lane >> 4;
;     const bf16_t* PROJ = (const bf16_t*)(ws + WS_PROJ); bf16_t* YSB = (bf16_t*)(ws + WS_YBR) + (size_t)NTOK * 1024;
;     const int b = unit >> 7, hd = (unit >> 4) & 7, qblk = unit & 15;
;     const size_t tokbase = (size_t)b * SEQ;
;     const int t0 = qblk * 128 + wave * 16;
;     LAS unsigned char* vb = lds + wave * 8192;
.LBB0_358:
	s_ashr_i32 s0, s30, 3
	s_andn2_b32 s0, s0, 31
	v_readlane_b32 s1, v254, 38
	s_add_i32 s2, s1, s0
	v_readlane_b32 s0, v254, 32
	v_readlane_b32 s1, v254, 33
	v_readlane_b32 s22, v254, 18
	s_and_b64 s[0:1], s[0:1], exec
	v_readlane_b32 s23, v254, 19
	v_mov_b32_e32 v1, v236
	s_cselect_b32 s7, s2, s30
	s_lshl_b32 s2, s7, 7
	v_readfirstlane_b32 s0, v1
	s_ashr_i32 s4, s0, 6
	s_ashr_i32 s0, s7, 7
	s_and_b32 s2, s2, 0x780
	s_lshl_b32 s5, s4, 4
	s_ashr_i32 s1, s0, 31
	s_add_i32 s5, s5, s2
	s_lshl_b64 s[0:1], s[0:1], 11
	s_ashr_i32 s2, s5, 31
	s_add_u32 s31, s0, s5
	s_waitcnt vmcnt(32)
	v_bfe_u32 v82, v1, 4, 2
	s_addc_u32 s34, s1, s2
	s_ashr_i32 s6, s5, 5
	s_mov_b64 s[2:3], -1
	s_cmp_gt_i32 s6, -1
	v_lshlrev_b32_e32 v155, 2, v82
	s_cbranch_scc1 .LBB0_360
	v_lshlrev_b32_e32 v2, 2, v82
	s_mov_b64 s[2:3], 0
